# state pass: s_setprio 2 for the H-role waves (the serial state chain), 0 again at the end
# speedup vs baseline: 1.0047x; 1.0047x over previous
.Lsp_hrole:
	s_setprio 2
	s_add_u32 s6, s96, s0
	s_addc_u32 s7, s97, 0
	v_lshl_add_u64 v[2:3], s[6:7], 0, v[14:15]
	s_add_u32 s6, s88, s0
	s_addc_u32 s7, s89, 0
	v_lshl_add_u64 v[6:7], s[6:7], 0, v[18:19]
	global_load_dwordx4 v[20:23], v[2:3], off
	global_load_dwordx4 v[24:27], v[2:3], off offset:1024
	global_load_dwordx2 v[28:29], v[6:7], off
	global_load_dwordx2 v[30:31], v[6:7], off offset:2048
	v_lshl_add_u64 v[2:3], v[2:3], 0, s[8:9]
	v_lshl_add_u64 v[6:7], v[6:7], 0, s[8:9]
	global_load_dwordx4 v[32:35], v[2:3], off
	global_load_dwordx4 v[36:39], v[2:3], off offset:1024
	global_load_dwordx2 v[40:41], v[6:7], off
	global_load_dwordx2 v[42:43], v[6:7], off offset:2048
	v_lshl_add_u64 v[2:3], v[2:3], 0, s[8:9]
	v_lshl_add_u64 v[6:7], v[6:7], 0, s[8:9]
	global_load_dwordx4 v[44:47], v[2:3], off
	global_load_dwordx4 v[48:51], v[2:3], off offset:1024
	global_load_dwordx2 v[52:53], v[6:7], off
	global_load_dwordx2 v[54:55], v[6:7], off offset:2048
	v_lshl_add_u64 v[2:3], v[2:3], 0, s[8:9]
	v_lshl_add_u64 v[6:7], v[6:7], 0, s[8:9]
	global_load_dwordx4 v[56:59], v[2:3], off
	global_load_dwordx4 v[60:63], v[2:3], off offset:1024
	global_load_dwordx2 v[64:65], v[6:7], off
	global_load_dwordx2 v[66:67], v[6:7], off offset:2048
	v_lshl_add_u64 v[2:3], v[2:3], 0, s[8:9]
	v_lshl_add_u64 v[6:7], v[6:7], 0, s[8:9]
	global_load_dwordx4 v[68:71], v[2:3], off
	global_load_dwordx4 v[72:75], v[2:3], off offset:1024
	global_load_dwordx2 v[76:77], v[6:7], off
	global_load_dwordx2 v[78:79], v[6:7], off offset:2048
	v_lshl_add_u64 v[2:3], v[2:3], 0, s[8:9]
	v_lshl_add_u64 v[6:7], v[6:7], 0, s[8:9]
	global_load_dwordx4 v[80:83], v[2:3], off
	global_load_dwordx4 v[84:87], v[2:3], off offset:1024
	global_load_dwordx2 v[88:89], v[6:7], off
	global_load_dwordx2 v[90:91], v[6:7], off offset:2048
	v_lshl_add_u64 v[2:3], v[2:3], 0, s[8:9]
	v_lshl_add_u64 v[6:7], v[6:7], 0, s[8:9]
	global_load_dwordx4 v[92:95], v[2:3], off
	global_load_dwordx4 v[96:99], v[2:3], off offset:1024
	global_load_dwordx2 v[100:101], v[6:7], off
	global_load_dwordx2 v[102:103], v[6:7], off offset:2048
	v_lshl_add_u64 v[2:3], v[2:3], 0, s[8:9]
	v_lshl_add_u64 v[6:7], v[6:7], 0, s[8:9]
	s_waitcnt lgkmcnt(0)
	s_barrier
	global_load_dwordx4 v[104:107], v[2:3], off
	global_load_dwordx4 v[108:111], v[2:3], off offset:1024
	global_load_dwordx2 v[112:113], v[6:7], off
	global_load_dwordx2 v[114:115], v[6:7], off offset:2048
	v_lshl_add_u64 v[2:3], v[2:3], 0, s[8:9]
	v_lshl_add_u64 v[6:7], v[6:7], 0, s[8:9]
	ds_read_b128 v[184:187], v10
	ds_read_b128 v[192:195], v10 offset:2560
	ds_read_b128 v[188:191], v10 offset:64
	ds_read_b128 v[196:199], v10 offset:2624
	s_waitcnt vmcnt(28)
	v_lshlrev_b32_e32 v200, 16, v28
	v_and_b32_e32 v201, 0xffff0000, v28
	v_lshlrev_b32_e32 v202, 16, v29
	v_and_b32_e32 v203, 0xffff0000, v29
	v_lshlrev_b32_e32 v204, 16, v30
	v_and_b32_e32 v205, 0xffff0000, v30
	v_lshlrev_b32_e32 v206, 16, v31
	v_and_b32_e32 v207, 0xffff0000, v31
	s_waitcnt lgkmcnt(2)
	v_mfma_f32_16x16x32_bf16 v[200:203], v[20:23], v[184:187], v[200:203]
	v_mfma_f32_16x16x32_bf16 v[204:207], v[20:23], v[192:195], v[204:207]
	s_waitcnt lgkmcnt(0)
	v_mfma_f32_16x16x32_bf16 v[200:203], v[24:27], v[188:191], v[200:203]
	v_mfma_f32_16x16x32_bf16 v[204:207], v[24:27], v[196:199], v[204:207]
	s_nop 6
	v_cvt_pk_bf16_f32 v200, v200, v201
	v_cvt_pk_bf16_f32 v201, v202, v203
	v_cvt_pk_bf16_f32 v204, v204, v205
	v_cvt_pk_bf16_f32 v205, v206, v207
	ds_write_b64 v11, v[200:201] offset:5120
	ds_write_b64 v11, v[204:205] offset:7680
	s_waitcnt lgkmcnt(0)
	s_barrier
	global_load_dwordx4 v[20:23], v[2:3], off
	global_load_dwordx4 v[24:27], v[2:3], off offset:1024
	global_load_dwordx2 v[28:29], v[6:7], off
	global_load_dwordx2 v[30:31], v[6:7], off offset:2048
	v_lshl_add_u64 v[2:3], v[2:3], 0, s[8:9]
	v_lshl_add_u64 v[6:7], v[6:7], 0, s[8:9]
	ds_read_b128 v[184:187], v10 offset:5120
	ds_read_b128 v[192:195], v10 offset:7680
	ds_read_b128 v[188:191], v10 offset:5184
	ds_read_b128 v[196:199], v10 offset:7744
	s_waitcnt vmcnt(28)
	v_lshlrev_b32_e32 v200, 16, v40
	v_and_b32_e32 v201, 0xffff0000, v40
	v_lshlrev_b32_e32 v202, 16, v41
	v_and_b32_e32 v203, 0xffff0000, v41
	v_lshlrev_b32_e32 v204, 16, v42
	v_and_b32_e32 v205, 0xffff0000, v42
	v_lshlrev_b32_e32 v206, 16, v43
	v_and_b32_e32 v207, 0xffff0000, v43
	s_waitcnt lgkmcnt(2)
	v_mfma_f32_16x16x32_bf16 v[200:203], v[32:35], v[184:187], v[200:203]
	v_mfma_f32_16x16x32_bf16 v[204:207], v[32:35], v[192:195], v[204:207]
	s_waitcnt lgkmcnt(0)
	v_mfma_f32_16x16x32_bf16 v[200:203], v[36:39], v[188:191], v[200:203]
	v_mfma_f32_16x16x32_bf16 v[204:207], v[36:39], v[196:199], v[204:207]
	s_nop 6
	v_cvt_pk_bf16_f32 v200, v200, v201
	v_cvt_pk_bf16_f32 v201, v202, v203
	v_cvt_pk_bf16_f32 v204, v204, v205
	v_cvt_pk_bf16_f32 v205, v206, v207
	ds_write_b64 v11, v[200:201]
	ds_write_b64 v11, v[204:205] offset:2560
	s_waitcnt lgkmcnt(0)
	s_barrier
	global_load_dwordx4 v[32:35], v[2:3], off
	global_load_dwordx4 v[36:39], v[2:3], off offset:1024
	global_load_dwordx2 v[40:41], v[6:7], off
	global_load_dwordx2 v[42:43], v[6:7], off offset:2048
	v_lshl_add_u64 v[2:3], v[2:3], 0, s[8:9]
	v_lshl_add_u64 v[6:7], v[6:7], 0, s[8:9]
	ds_read_b128 v[184:187], v10
	ds_read_b128 v[192:195], v10 offset:2560
	ds_read_b128 v[188:191], v10 offset:64
	ds_read_b128 v[196:199], v10 offset:2624
	s_waitcnt vmcnt(28)
	v_lshlrev_b32_e32 v200, 16, v52
	v_and_b32_e32 v201, 0xffff0000, v52
	v_lshlrev_b32_e32 v202, 16, v53
	v_and_b32_e32 v203, 0xffff0000, v53
	v_lshlrev_b32_e32 v204, 16, v54
	v_and_b32_e32 v205, 0xffff0000, v54
	v_lshlrev_b32_e32 v206, 16, v55
	v_and_b32_e32 v207, 0xffff0000, v55
	s_waitcnt lgkmcnt(2)
	v_mfma_f32_16x16x32_bf16 v[200:203], v[44:47], v[184:187], v[200:203]
	v_mfma_f32_16x16x32_bf16 v[204:207], v[44:47], v[192:195], v[204:207]
	s_waitcnt lgkmcnt(0)
	v_mfma_f32_16x16x32_bf16 v[200:203], v[48:51], v[188:191], v[200:203]
	v_mfma_f32_16x16x32_bf16 v[204:207], v[48:51], v[196:199], v[204:207]
	s_nop 6
	v_cvt_pk_bf16_f32 v200, v200, v201
	v_cvt_pk_bf16_f32 v201, v202, v203
	v_cvt_pk_bf16_f32 v204, v204, v205
	v_cvt_pk_bf16_f32 v205, v206, v207
	ds_write_b64 v11, v[200:201] offset:5120
	ds_write_b64 v11, v[204:205] offset:7680
	s_waitcnt lgkmcnt(0)
	s_barrier
	global_load_dwordx4 v[44:47], v[2:3], off
	global_load_dwordx4 v[48:51], v[2:3], off offset:1024
	global_load_dwordx2 v[52:53], v[6:7], off
	global_load_dwordx2 v[54:55], v[6:7], off offset:2048
	v_lshl_add_u64 v[2:3], v[2:3], 0, s[8:9]
	v_lshl_add_u64 v[6:7], v[6:7], 0, s[8:9]
	ds_read_b128 v[184:187], v10 offset:5120
	ds_read_b128 v[192:195], v10 offset:7680
	ds_read_b128 v[188:191], v10 offset:5184
	ds_read_b128 v[196:199], v10 offset:7744
	s_waitcnt vmcnt(28)
	v_lshlrev_b32_e32 v200, 16, v64
	v_and_b32_e32 v201, 0xffff0000, v64
	v_lshlrev_b32_e32 v202, 16, v65
	v_and_b32_e32 v203, 0xffff0000, v65
	v_lshlrev_b32_e32 v204, 16, v66
	v_and_b32_e32 v205, 0xffff0000, v66
	v_lshlrev_b32_e32 v206, 16, v67
	v_and_b32_e32 v207, 0xffff0000, v67
	s_waitcnt lgkmcnt(2)
	v_mfma_f32_16x16x32_bf16 v[200:203], v[56:59], v[184:187], v[200:203]
	v_mfma_f32_16x16x32_bf16 v[204:207], v[56:59], v[192:195], v[204:207]
	s_waitcnt lgkmcnt(0)
	v_mfma_f32_16x16x32_bf16 v[200:203], v[60:63], v[188:191], v[200:203]
	v_mfma_f32_16x16x32_bf16 v[204:207], v[60:63], v[196:199], v[204:207]
	s_nop 6
	v_cvt_pk_bf16_f32 v200, v200, v201
	v_cvt_pk_bf16_f32 v201, v202, v203
	v_cvt_pk_bf16_f32 v204, v204, v205
	v_cvt_pk_bf16_f32 v205, v206, v207
	ds_write_b64 v11, v[200:201]
	ds_write_b64 v11, v[204:205] offset:2560
	s_waitcnt lgkmcnt(0)
	s_barrier
	global_load_dwordx4 v[56:59], v[2:3], off
	global_load_dwordx4 v[60:63], v[2:3], off offset:1024
	global_load_dwordx2 v[64:65], v[6:7], off
	global_load_dwordx2 v[66:67], v[6:7], off offset:2048
	v_lshl_add_u64 v[2:3], v[2:3], 0, s[8:9]
	v_lshl_add_u64 v[6:7], v[6:7], 0, s[8:9]
	ds_read_b128 v[184:187], v10
	ds_read_b128 v[192:195], v10 offset:2560
	ds_read_b128 v[188:191], v10 offset:64
	ds_read_b128 v[196:199], v10 offset:2624
	s_waitcnt vmcnt(28)
	v_lshlrev_b32_e32 v200, 16, v76
	v_and_b32_e32 v201, 0xffff0000, v76
	v_lshlrev_b32_e32 v202, 16, v77
	v_and_b32_e32 v203, 0xffff0000, v77
	v_lshlrev_b32_e32 v204, 16, v78
	v_and_b32_e32 v205, 0xffff0000, v78
	v_lshlrev_b32_e32 v206, 16, v79
	v_and_b32_e32 v207, 0xffff0000, v79
	s_waitcnt lgkmcnt(2)
	v_mfma_f32_16x16x32_bf16 v[200:203], v[68:71], v[184:187], v[200:203]
	v_mfma_f32_16x16x32_bf16 v[204:207], v[68:71], v[192:195], v[204:207]
	s_waitcnt lgkmcnt(0)
	v_mfma_f32_16x16x32_bf16 v[200:203], v[72:75], v[188:191], v[200:203]
	v_mfma_f32_16x16x32_bf16 v[204:207], v[72:75], v[196:199], v[204:207]
	s_nop 6
	v_cvt_pk_bf16_f32 v200, v200, v201
	v_cvt_pk_bf16_f32 v201, v202, v203
	v_cvt_pk_bf16_f32 v204, v204, v205
	v_cvt_pk_bf16_f32 v205, v206, v207
	ds_write_b64 v11, v[200:201] offset:5120
	ds_write_b64 v11, v[204:205] offset:7680
	s_waitcnt lgkmcnt(0)
	s_barrier
	global_load_dwordx4 v[68:71], v[2:3], off
	global_load_dwordx4 v[72:75], v[2:3], off offset:1024
	global_load_dwordx2 v[76:77], v[6:7], off
	global_load_dwordx2 v[78:79], v[6:7], off offset:2048
	v_lshl_add_u64 v[2:3], v[2:3], 0, s[8:9]
	v_lshl_add_u64 v[6:7], v[6:7], 0, s[8:9]
	ds_read_b128 v[184:187], v10 offset:5120
	ds_read_b128 v[192:195], v10 offset:7680
	ds_read_b128 v[188:191], v10 offset:5184
	ds_read_b128 v[196:199], v10 offset:7744
	s_waitcnt vmcnt(28)
	v_lshlrev_b32_e32 v200, 16, v88
	v_and_b32_e32 v201, 0xffff0000, v88
	v_lshlrev_b32_e32 v202, 16, v89
	v_and_b32_e32 v203, 0xffff0000, v89
	v_lshlrev_b32_e32 v204, 16, v90
	v_and_b32_e32 v205, 0xffff0000, v90
	v_lshlrev_b32_e32 v206, 16, v91
	v_and_b32_e32 v207, 0xffff0000, v91
	s_waitcnt lgkmcnt(2)
	v_mfma_f32_16x16x32_bf16 v[200:203], v[80:83], v[184:187], v[200:203]
	v_mfma_f32_16x16x32_bf16 v[204:207], v[80:83], v[192:195], v[204:207]
	s_waitcnt lgkmcnt(0)
	v_mfma_f32_16x16x32_bf16 v[200:203], v[84:87], v[188:191], v[200:203]
	v_mfma_f32_16x16x32_bf16 v[204:207], v[84:87], v[196:199], v[204:207]
	s_nop 6
	v_cvt_pk_bf16_f32 v200, v200, v201
	v_cvt_pk_bf16_f32 v201, v202, v203
	v_cvt_pk_bf16_f32 v204, v204, v205
	v_cvt_pk_bf16_f32 v205, v206, v207
	ds_write_b64 v11, v[200:201]
	ds_write_b64 v11, v[204:205] offset:2560
	s_waitcnt lgkmcnt(0)
	s_barrier
	global_load_dwordx4 v[80:83], v[2:3], off
	global_load_dwordx4 v[84:87], v[2:3], off offset:1024
	global_load_dwordx2 v[88:89], v[6:7], off
	global_load_dwordx2 v[90:91], v[6:7], off offset:2048
	v_lshl_add_u64 v[2:3], v[2:3], 0, s[8:9]
	v_lshl_add_u64 v[6:7], v[6:7], 0, s[8:9]
	ds_read_b128 v[184:187], v10
	ds_read_b128 v[192:195], v10 offset:2560
	ds_read_b128 v[188:191], v10 offset:64
	ds_read_b128 v[196:199], v10 offset:2624
	s_waitcnt vmcnt(28)
	v_lshlrev_b32_e32 v200, 16, v100
	v_and_b32_e32 v201, 0xffff0000, v100
	v_lshlrev_b32_e32 v202, 16, v101
	v_and_b32_e32 v203, 0xffff0000, v101
	v_lshlrev_b32_e32 v204, 16, v102
	v_and_b32_e32 v205, 0xffff0000, v102
	v_lshlrev_b32_e32 v206, 16, v103
	v_and_b32_e32 v207, 0xffff0000, v103
	s_waitcnt lgkmcnt(2)
	v_mfma_f32_16x16x32_bf16 v[200:203], v[92:95], v[184:187], v[200:203]
	v_mfma_f32_16x16x32_bf16 v[204:207], v[92:95], v[192:195], v[204:207]
	s_waitcnt lgkmcnt(0)
	v_mfma_f32_16x16x32_bf16 v[200:203], v[96:99], v[188:191], v[200:203]
	v_mfma_f32_16x16x32_bf16 v[204:207], v[96:99], v[196:199], v[204:207]
	s_nop 6
	v_cvt_pk_bf16_f32 v200, v200, v201
	v_cvt_pk_bf16_f32 v201, v202, v203
	v_cvt_pk_bf16_f32 v204, v204, v205
	v_cvt_pk_bf16_f32 v205, v206, v207
	ds_write_b64 v11, v[200:201] offset:5120
	ds_write_b64 v11, v[204:205] offset:7680
	s_waitcnt lgkmcnt(0)
	s_barrier
	global_load_dwordx4 v[92:95], v[2:3], off
	global_load_dwordx4 v[96:99], v[2:3], off offset:1024
	global_load_dwordx2 v[100:101], v[6:7], off
	global_load_dwordx2 v[102:103], v[6:7], off offset:2048
	v_lshl_add_u64 v[2:3], v[2:3], 0, s[8:9]
	v_lshl_add_u64 v[6:7], v[6:7], 0, s[8:9]
	ds_read_b128 v[184:187], v10 offset:5120
	ds_read_b128 v[192:195], v10 offset:7680
	ds_read_b128 v[188:191], v10 offset:5184
	ds_read_b128 v[196:199], v10 offset:7744
	s_waitcnt vmcnt(28)
	v_lshlrev_b32_e32 v200, 16, v112
	v_and_b32_e32 v201, 0xffff0000, v112
	v_lshlrev_b32_e32 v202, 16, v113
	v_and_b32_e32 v203, 0xffff0000, v113
	v_lshlrev_b32_e32 v204, 16, v114
	v_and_b32_e32 v205, 0xffff0000, v114
	v_lshlrev_b32_e32 v206, 16, v115
	v_and_b32_e32 v207, 0xffff0000, v115
	s_waitcnt lgkmcnt(2)
	v_mfma_f32_16x16x32_bf16 v[200:203], v[104:107], v[184:187], v[200:203]
	v_mfma_f32_16x16x32_bf16 v[204:207], v[104:107], v[192:195], v[204:207]
	s_waitcnt lgkmcnt(0)
	v_mfma_f32_16x16x32_bf16 v[200:203], v[108:111], v[188:191], v[200:203]
	v_mfma_f32_16x16x32_bf16 v[204:207], v[108:111], v[196:199], v[204:207]
	s_nop 6
	v_cvt_pk_bf16_f32 v200, v200, v201
	v_cvt_pk_bf16_f32 v201, v202, v203
	v_cvt_pk_bf16_f32 v204, v204, v205
	v_cvt_pk_bf16_f32 v205, v206, v207
	ds_write_b64 v11, v[200:201]
	ds_write_b64 v11, v[204:205] offset:2560
	s_waitcnt lgkmcnt(0)
	s_barrier
	s_mov_b32 s10, 6

.Lsp_done:
	s_setprio 0
